# NA window tiles: second 16-key half of the exp2/convert work issued in the shadows of the first three PV/row-sum MFMAs
# baseline (speedup 1.0000x reference)
.Lna_541:
	v_exp_f32_e32 v0, v14
	v_exp_f32_e32 v14, v15
	v_exp_f32_e32 v15, v80
	v_exp_f32_e32 v81, v81
	v_exp_f32_e32 v82, v82
	v_exp_f32_e32 v83, v83
	v_exp_f32_e32 v94, v84
	v_exp_f32_e32 v95, v85
	v_cvt_pk_bf16_f32 v80, v0, v14
	v_cvt_pk_bf16_f32 v81, v15, v81
	v_cvt_pk_bf16_f32 v82, v82, v83
	v_cvt_pk_bf16_f32 v83, v94, v95
	s_setprio 1
	s_waitcnt lgkmcnt(0)
	v_mfma_f32_32x32x16_bf16 v[32:47], v[10:13], v[80:83], v[32:47]
	v_exp_f32_e32 v84, v86
	v_exp_f32_e32 v85, v87
	v_exp_f32_e32 v86, v88
	v_mfma_f32_32x32x16_bf16 v[16:31], v[96:99], v[80:83], v[16:31]
	v_exp_f32_e32 v87, v89
	v_exp_f32_e32 v88, v90
	v_exp_f32_e32 v89, v91
	v_mfma_f32_32x32x16_bf16 v[48:63], v[116:119], v[80:83], v[48:63]
	v_exp_f32_e32 v90, v92
	v_exp_f32_e32 v91, v93
	v_cvt_pk_bf16_f32 v84, v84, v85
	v_cvt_pk_bf16_f32 v85, v86, v87
	v_cvt_pk_bf16_f32 v86, v88, v89
	v_cvt_pk_bf16_f32 v87, v90, v91
	s_nop 1
	v_mfma_f32_32x32x16_bf16 v[32:47], v[6:9], v[84:87], v[32:47]
	v_mfma_f32_32x32x16_bf16 v[48:63], v[116:119], v[84:87], v[48:63]
	v_mfma_f32_32x32x16_bf16 v[16:31], v[2:5], v[84:87], v[16:31]
	s_setprio 0
